# loop-edge edits on the attention loop: back edge rotated (loop-carried copies in front of the closing barrier, one taken branch behind it), first half-step rescale branch on the threshold SCC directly
# baseline (speedup 1.0000x reference)
; __device__ __forceinline__ void partialSM(f32x16& p0, f32x16& p1, float& m_reg, float& mn, float& alpha, bool rs) {
;     float pmax = p0[0]; for (int r = 1; r < 16; ++r) pmax = fmaxf(pmax, p0[r]); for (int r = 0; r < 16; ++r) pmax = fmaxf(pmax, p1[r]);
;     if (!rs) pmax = -__builtin_inff();
;     { auto rr = __builtin_amdgcn_permlane32_swap(__float_as_uint(pmax), __float_as_uint(pmax), false, false);
;       pmax = fmaxf(__uint_as_float(rr[0]), __uint_as_float(rr[1])); }
;     constexpr float C2 = 1.4426950408889634f * SCALE;
;     if (__builtin_expect(__all((pmax - m_reg) * SCALE <= THR), 1)) { mn = m_reg; alpha = 1.f; }
;     else { mn = fmaxf(m_reg, pmax); alpha = __builtin_amdgcn_exp2f((m_reg - mn) * C2); m_reg = mn; }
.LBB0_91:
	s_add_i32 s0, s3, -2
	s_lshr_b32 s8, s0, 2
	s_cmp_ge_i32 s8, s44
	s_cselect_b64 s[0:1], -1, 0
	s_lshl_b32 s8, 1, s8
	v_and_b32_e32 v148, s8, v165
	v_cmp_ne_u32_e32 vcc, 0, v148
	v_max_f32_e32 v148, v83, v83
	v_max_f32_e32 v149, v82, v82
	v_max_f32_e32 v148, v149, v148
	v_max3_f32 v148, v148, v84, v85
	v_max3_f32 v148, v148, v86, v87
	v_max3_f32 v148, v148, v88, v89
	v_max3_f32 v148, v148, v90, v91
	v_max3_f32 v148, v148, v92, v93
	v_max3_f32 v148, v148, v94, v95
	v_max3_f32 v148, v148, v96, v97
	v_max3_f32 v148, v148, v66, v67
	v_max3_f32 v148, v148, v68, v69
	v_max3_f32 v148, v148, v70, v71
	v_max3_f32 v148, v148, v72, v73
	v_max3_f32 v148, v148, v74, v75
	v_max3_f32 v148, v148, v76, v77
	v_max3_f32 v148, v148, v78, v79
	s_or_b64 s[40:41], s[0:1], vcc
	v_max3_f32 v148, v148, v80, v81
	v_cndmask_b32_e64 v148, v220, v148, s[40:41]
	v_mov_b32_e32 v149, v148
	s_nop 1
	v_permlane32_swap_b32_e32 v148, v149
	v_max_f32_e32 v149, v149, v149
	v_max_f32_e32 v148, v148, v148
	v_max_f32_e32 v148, v148, v149
	v_sub_f32_e32 v149, v148, v198
	v_mul_f32_e32 v149, 0x3db504f3, v149
	v_cmp_ge_f32_e32 vcc, s91, v149
	v_max_f32_e32 v149, v198, v198
	v_max_f32_e32 v148, v149, v148
	v_sub_f32_e32 v149, v198, v148
	v_mul_f32_e32 v149, 0x3e0293ee, v149
	v_exp_f32_e32 v149, v149
	s_cmp_eq_u64 vcc, exec
	s_cselect_b64 s[42:43], -1, 0
	v_cndmask_b32_e64 v202, v149, 1.0, s[42:43]
	s_cbranch_scc1 .LBB0_95
	s_and_saveexec_b64 s[0:1], s[38:39]
	ds_write_b32 v187, v202 offset:128
	s_or_b64 exec, exec, s[0:1]
	s_waitcnt lgkmcnt(0)
	ds_read_b128 v[150:153], v186 offset:224
	ds_read_b128 v[154:157], v186 offset:192
	ds_read_b128 v[158:161], v186 offset:160
	ds_read_b128 v[172:175], v186 offset:128
	s_waitcnt lgkmcnt(3)
	v_pk_mul_f32 v[64:65], v[64:65], v[152:153]
	s_waitcnt lgkmcnt(2)
	v_pk_mul_f32 v[60:61], v[60:61], v[156:157]
	s_waitcnt lgkmcnt(1)
	v_pk_mul_f32 v[56:57], v[56:57], v[160:161]
	s_waitcnt lgkmcnt(0)
	v_pk_mul_f32 v[52:53], v[52:53], v[174:175]
	v_pk_mul_f32 v[62:63], v[62:63], v[150:151]
	v_pk_mul_f32 v[58:59], v[58:59], v[154:155]
	v_pk_mul_f32 v[54:55], v[54:55], v[158:159]
	v_pk_mul_f32 v[50:51], v[50:51], v[172:173]
	v_pk_mul_f32 v[48:49], v[48:49], v[152:153]
	v_pk_mul_f32 v[44:45], v[44:45], v[156:157]
	v_pk_mul_f32 v[40:41], v[40:41], v[160:161]
	v_pk_mul_f32 v[36:37], v[36:37], v[174:175]
	v_pk_mul_f32 v[46:47], v[46:47], v[150:151]
	v_pk_mul_f32 v[42:43], v[42:43], v[154:155]
	v_pk_mul_f32 v[38:39], v[38:39], v[158:159]
	v_pk_mul_f32 v[34:35], v[34:35], v[172:173]
	v_pk_mul_f32 v[32:33], v[32:33], v[152:153]
	v_pk_mul_f32 v[28:29], v[28:29], v[156:157]
	v_pk_mul_f32 v[24:25], v[24:25], v[160:161]
	v_pk_mul_f32 v[20:21], v[20:21], v[174:175]
	v_pk_mul_f32 v[30:31], v[30:31], v[150:151]
	v_pk_mul_f32 v[26:27], v[26:27], v[154:155]
	v_pk_mul_f32 v[22:23], v[22:23], v[158:159]
	v_pk_mul_f32 v[18:19], v[18:19], v[172:173]
	v_pk_mul_f32 v[16:17], v[16:17], v[152:153]
	v_pk_mul_f32 v[12:13], v[12:13], v[156:157]
	v_pk_mul_f32 v[8:9], v[8:9], v[160:161]
	v_pk_mul_f32 v[4:5], v[4:5], v[174:175]
	v_pk_mul_f32 v[14:15], v[14:15], v[150:151]
	v_pk_mul_f32 v[10:11], v[10:11], v[154:155]
	v_pk_mul_f32 v[6:7], v[6:7], v[158:159]
	v_pk_mul_f32 v[2:3], v[2:3], v[172:173]

; __device__ __forceinline__ void partialSM(f32x16& p0, f32x16& p1, float& m_reg, float& mn, float& alpha, bool rs) {
;     ...
;     const float mnL = rs ? -mn * C2 : -__builtin_inff();
;     for (int r = 0; r < 16; ++r) p0[r] = fmaf(p0[r], C2, mnL); for (int r = 0; r < 16; ++r) p1[r] = fmaf(p1[r], C2, mnL);
;     for (int r = 0; r < 16; ++r) p0[r] = __builtin_amdgcn_exp2f(p0[r]);
; __device__ __forceinline__ void finishSM(f32x16& p0, f32x16& p1, float alpha, float& l_reg, bf16x8& pa0, bf16x8& pa1, bf16x8& pa2, bf16x8& pa3) {
;     ...
;     l_reg = l_reg * alpha + ps;
; __device__ __forceinline__ void moba_block(const BlockRef& cur, const BlockRef& nxt, char* lds, Seam& S) {
;     ...
;     for (int t = 1; t + 1 < NT; t += 2) {
;         HALF_STEP(pB0, pB1, mnB, alB, pA0, pA1, alA, t, 1, 0, 0);
;         HALF_STEP(pA0, pA1, mnA, alA, pB0, pB1, alB, t + 1, 0, 1, 1);
;     }
.LBB0_105:
	v_cndmask_b32_e64 v198, v100, v179, s[42:43]
	v_mul_f32_e32 v100, 0xbe0293ee, v198
	v_cndmask_b32_e64 v100, v220, v100, s[40:41]
	v_mov_b32_e32 v101, v100
	v_fmamk_f32 v82, v82, 0x3e0293ee, v100
	v_fmamk_f32 v83, v83, 0x3e0293ee, v100
	v_fmamk_f32 v84, v84, 0x3e0293ee, v100
	v_fmamk_f32 v85, v85, 0x3e0293ee, v100
	v_fmamk_f32 v86, v86, 0x3e0293ee, v100
	v_fmamk_f32 v87, v87, 0x3e0293ee, v100
	v_fmamk_f32 v88, v88, 0x3e0293ee, v100
	v_fmamk_f32 v89, v89, 0x3e0293ee, v100
	v_fmamk_f32 v90, v90, 0x3e0293ee, v100
	v_fmamk_f32 v91, v91, 0x3e0293ee, v100
	v_fmamk_f32 v92, v92, 0x3e0293ee, v100
	v_fmamk_f32 v93, v93, 0x3e0293ee, v100
	v_fmamk_f32 v94, v94, 0x3e0293ee, v100
	v_fmamk_f32 v95, v95, 0x3e0293ee, v100
	v_fmamk_f32 v96, v96, 0x3e0293ee, v100
	v_fmac_f32_e32 v101, 0x3e0293ee, v97
	v_exp_f32_e32 v231, v82
	v_exp_f32_e32 v233, v83
	v_exp_f32_e32 v229, v84
	v_exp_f32_e32 v232, v85
	v_exp_f32_e32 v228, v86
	v_exp_f32_e32 v230, v87
	v_exp_f32_e32 v226, v88
	v_exp_f32_e32 v227, v89
	v_exp_f32_e32 v223, v90
	v_exp_f32_e32 v225, v91
	v_exp_f32_e32 v209, v92
	v_exp_f32_e32 v224, v93
	v_exp_f32_e32 v206, v94
	v_exp_f32_e32 v208, v95
	v_exp_f32_e32 v205, v96
	v_exp_f32_e32 v207, v101
	v_pk_fma_f32 v[178:179], v[66:67], s[20:21], v[100:101] op_sel_hi:[1,0,0]
	v_add_f32_e32 v66, v199, v200
	v_fmac_f32_e32 v66, v196, v189
	v_add_f32_e32 v189, v203, v204
	s_add_i32 s0, s3, 2
	s_add_i32 s1, s3, 1
	s_addk_i32 s7, 0x80
	v_pk_fma_f32 v[162:163], v[68:69], s[20:21], v[100:101] op_sel_hi:[1,0,0]
	v_pk_fma_f32 v[158:159], v[70:71], s[20:21], v[100:101] op_sel_hi:[1,0,0]
	v_pk_fma_f32 v[156:157], v[72:73], s[20:21], v[100:101] op_sel_hi:[1,0,0]
	v_pk_fma_f32 v[152:153], v[74:75], s[20:21], v[100:101] op_sel_hi:[1,0,0]
	v_pk_fma_f32 v[180:181], v[76:77], s[20:21], v[100:101] op_sel_hi:[1,0,0]
	v_pk_fma_f32 v[160:161], v[78:79], s[20:21], v[100:101] op_sel_hi:[1,0,0]
	v_pk_fma_f32 v[154:155], v[80:81], s[20:21], v[100:101] op_sel_hi:[1,0,0]
	v_fmac_f32_e32 v189, v66, v202
	s_cmp_lt_u32 s1, s2
	v_add_u32_e32 v197, 0xffffff80, v197
	s_mov_b32 s3, s0
	v_mov_b32_e32 v196, v201
	s_waitcnt vmcnt(0)
	s_waitcnt lgkmcnt(0)
	s_barrier
	s_cbranch_scc1 .LBB0_89
